# P3: list counts parked in LDS by the prescan, per-unit count read from LDS instead of global
# baseline (speedup 1.0000x reference)
.LBB0_793:
	s_or_b64 exec, exec, s[0:1]
	s_waitcnt lgkmcnt(0)
	v_mov_b32_e32 v0, v192
	s_barrier
	v_mov_b32_e32 v4, 0
	v_mov_b32_e32 v0, v192
	s_nop 0
	v_ashrrev_i32_e32 v1, 31, v0
	v_lshl_add_u64 v[2:3], v[0:1], 2, s[78:79]
	s_barrier
	global_load_dword v2, v[2:3], off
	v_lshl_add_u32 v1, v0, 2, 0
	v_add_u32_e32 v1, 0x22820, v1
	v_cmp_lt_i32_e32 vcc, 0, v0
	s_waitcnt vmcnt(0)
	ds_write_b32 v1, v2 offset:2048
	v_add_u32_e32 v2, 0xff, v2
	v_lshrrev_b32_e32 v2, 8, v2
	v_add_u32_e32 v2, 1, v2
	ds_write_b32 v1, v2
	s_waitcnt lgkmcnt(0)
	s_barrier
	ds_read_b32 v3, v1
	v_mov_b32_e32 v2, 0
	s_and_saveexec_b64 s[0:1], vcc
	v_add_u32_e32 v4, -4, v1
	ds_read_b32 v4, v4
	s_or_b64 exec, exec, s[0:1]
	s_waitcnt lgkmcnt(0)
	v_add_u32_e32 v3, v4, v3
	s_barrier
	ds_write_b32 v1, v3
	s_waitcnt lgkmcnt(0)
	s_barrier
	ds_read_b32 v3, v1
	v_cmp_lt_i32_e32 vcc, 1, v0
	s_and_saveexec_b64 s[0:1], vcc
	v_add_u32_e32 v2, -8, v1
	ds_read_b32 v2, v2
	s_or_b64 exec, exec, s[0:1]
	s_waitcnt lgkmcnt(0)
	v_add_u32_e32 v2, v2, v3
	s_barrier
	ds_write_b32 v1, v2
	s_waitcnt lgkmcnt(0)
	s_barrier
	ds_read_b32 v3, v1
	v_cmp_lt_i32_e32 vcc, 3, v0
	v_mov_b32_e32 v2, 0
	v_mov_b32_e32 v4, 0
	s_and_saveexec_b64 s[0:1], vcc
	v_add_u32_e32 v4, -16, v1
	ds_read_b32 v4, v4
	s_or_b64 exec, exec, s[0:1]
	s_waitcnt lgkmcnt(0)
	v_add_u32_e32 v3, v4, v3
	s_barrier
	ds_write_b32 v1, v3
	s_waitcnt lgkmcnt(0)
	s_barrier
	ds_read_b32 v3, v1
	v_cmp_lt_i32_e32 vcc, 7, v0
	s_and_saveexec_b64 s[0:1], vcc
	v_subrev_u32_e32 v2, 32, v1
	ds_read_b32 v2, v2
	s_or_b64 exec, exec, s[0:1]
	s_waitcnt lgkmcnt(0)
	v_add_u32_e32 v2, v2, v3
	s_barrier
	ds_write_b32 v1, v2
	s_waitcnt lgkmcnt(0)
	s_barrier
	ds_read_b32 v3, v1
	v_cmp_lt_i32_e32 vcc, 15, v0
	v_mov_b32_e32 v2, 0
	v_mov_b32_e32 v4, 0
	s_and_saveexec_b64 s[0:1], vcc
	v_subrev_u32_e32 v4, 64, v1
	ds_read_b32 v4, v4
	s_or_b64 exec, exec, s[0:1]
	s_waitcnt lgkmcnt(0)
	v_add_u32_e32 v3, v4, v3
	s_barrier
	ds_write_b32 v1, v3
	s_waitcnt lgkmcnt(0)
	s_barrier
	ds_read_b32 v3, v1
	v_cmp_lt_i32_e32 vcc, 31, v0
	s_and_saveexec_b64 s[0:1], vcc
	v_add_u32_e32 v2, 0xffffff80, v1
	ds_read_b32 v2, v2
	s_or_b64 exec, exec, s[0:1]
	s_waitcnt lgkmcnt(0)
	v_add_u32_e32 v2, v2, v3
	s_barrier
	ds_write_b32 v1, v2
	s_waitcnt lgkmcnt(0)
	s_barrier
	ds_read_b32 v3, v1
	v_cmp_lt_i32_e32 vcc, 63, v0
	v_mov_b32_e32 v2, 0
	v_mov_b32_e32 v4, 0
	s_and_saveexec_b64 s[0:1], vcc
	v_add_u32_e32 v4, 0xffffff00, v1
	ds_read_b32 v4, v4
	s_or_b64 exec, exec, s[0:1]
	s_waitcnt lgkmcnt(0)
	v_add_u32_e32 v3, v4, v3
	s_barrier
	ds_write_b32 v1, v3
	s_waitcnt lgkmcnt(0)
	s_barrier
	ds_read_b32 v3, v1
	s_movk_i32 s0, 0x7f
	v_cmp_lt_i32_e32 vcc, s0, v0
	s_and_saveexec_b64 s[0:1], vcc
	v_add_u32_e32 v2, 0xfffffe00, v1
	ds_read_b32 v2, v2
	s_or_b64 exec, exec, s[0:1]
	s_waitcnt lgkmcnt(0)
	v_add_u32_e32 v2, v2, v3
	s_barrier
	ds_write_b32 v1, v2
	s_waitcnt lgkmcnt(0)
	s_barrier
	ds_read_b32 v2, v1
	s_movk_i32 s0, 0xff
	v_cmp_lt_i32_e32 vcc, s0, v0
	v_mov_b32_e32 v3, 0
	s_and_saveexec_b64 s[0:1], vcc
	v_add_u32_e32 v3, 0xfffffc00, v1
	ds_read_b32 v3, v3
	s_or_b64 exec, exec, s[0:1]
	s_waitcnt lgkmcnt(0)
	v_add_u32_e32 v2, v3, v2
	s_barrier
	ds_write_b32 v1, v2
	s_waitcnt lgkmcnt(0)
	s_barrier
	ds_read_b32 v1, v1
	s_add_i32 s2, 0, 0x22000
	v_lshl_add_u32 v2, v0, 2, s2
	v_cmp_eq_u32_e32 vcc, 0, v0
	s_waitcnt lgkmcnt(0)
	ds_write_b32 v2, v1 offset:4
	s_and_saveexec_b64 s[0:1], vcc
	v_mov_b32_e32 v1, 0
	v_mov_b32_e32 v2, s2
	ds_write_b32 v2, v1
	s_or_b64 exec, exec, s[0:1]
	s_add_i32 s0, 0, 0x22800
	v_mov_b32_e32 v1, s0
	s_waitcnt lgkmcnt(0)
	s_barrier
	ds_read_b32 v2, v1
	v_and_b32_e32 v1, 63, v0
	s_waitcnt lgkmcnt(0)
	v_cmp_ge_i32_e32 vcc, s90, v2
	v_readfirstlane_b32 s18, v2
	s_cbranch_vccnz .LBB0_846
	s_movk_i32 s1, 0x1ff
	s_mov_b32 s0, 0

.LBB0_828:
	s_add_i32 s7, s1, s0
	s_add_i32 s7, s7, 1
	s_ashr_i32 s7, s7, 1
	s_lshl_b32 s8, s7, 2
	s_add_i32 s8, s8, 0
	s_add_i32 s8, s8, 0x22000
	v_mov_b32_e32 v0, s8
	ds_read_b32 v0, v0
	s_add_i32 s8, s7, -1
	s_waitcnt lgkmcnt(0)
	v_readfirstlane_b32 s9, v0
	s_cmp_gt_i32 s9, s6
	s_cselect_b32 s1, s8, s1
	s_cselect_b32 s0, s0, s7
	s_cmp_lt_i32 s0, s1
	s_cbranch_scc1 .LBB0_828
	s_lshl_b32 s98, s0, 2
	s_add_i32 s98, s98, 0x23020
	v_mov_b32_e32 v20, s98
	ds_read_b32 v20, v20
	s_lshl_b32 s1, s0, 2
	s_lshl_b32 s7, s0, 8
	s_add_i32 s1, s1, 0
	s_and_b32 s16, s7, 0x3f00
	s_add_i32 s1, s1, 0x22000
	s_lshl_b32 s7, s16, 11
	v_readlane_b32 s8, v254, 43
	v_readlane_b32 s9, v254, 44
	s_add_u32 s17, s8, s7
	s_addc_u32 s23, s9, 0
	s_lshl_b32 s8, s0, 1
	s_and_b32 s8, s8, 0xffffff80
	s_ashr_i32 s9, s8, 31
	s_lshl_b64 s[8:9], s[8:9], 1
	s_add_u32 s24, s17, s8
	s_addc_u32 s25, s23, s9
	v_readlane_b32 s26, v254, 45
	v_readlane_b32 s27, v254, 46
	s_add_u32 s7, s26, s7
	s_addc_u32 s17, s27, 0
	s_add_u32 s8, s7, s8
	v_mov_b32_e32 v195, v199
	s_addc_u32 s9, s17, s9
	v_lshl_add_u64 v[0:1], s[24:25], 0, v[194:195]
	v_lshl_add_u64 v[2:3], s[8:9], 0, v[194:195]
	v_lshl_add_u64 v[4:5], v[0:1], 0, v[200:201]
	v_lshl_add_u64 v[6:7], v[2:3], 0, v[200:201]
	global_load_dwordx4 v[96:99], v[4:5], off
	global_load_dwordx4 v[100:103], v[6:7], off
	v_lshl_add_u64 v[4:5], v[0:1], 0, v[202:203]
	v_lshl_add_u64 v[6:7], v[2:3], 0, v[202:203]
	global_load_dwordx4 v[104:107], v[4:5], off
	global_load_dwordx4 v[108:111], v[6:7], off
	v_lshl_add_u64 v[4:5], v[0:1], 0, v[204:205]
	v_lshl_add_u64 v[6:7], v[2:3], 0, v[204:205]
	global_load_dwordx4 v[112:115], v[4:5], off
	global_load_dwordx4 v[116:119], v[6:7], off
	v_lshl_add_u64 v[4:5], v[0:1], 0, v[206:207]
	v_lshl_add_u64 v[6:7], v[2:3], 0, v[206:207]
	global_load_dwordx4 v[120:123], v[4:5], off
	global_load_dwordx4 v[124:127], v[6:7], off
	v_lshl_add_u64 v[4:5], v[0:1], 0, v[208:209]
	v_lshl_add_u64 v[6:7], v[2:3], 0, v[208:209]
	global_load_dwordx4 v[128:131], v[4:5], off
	global_load_dwordx4 v[132:135], v[6:7], off
	v_lshl_add_u64 v[4:5], v[0:1], 0, v[210:211]
	v_lshl_add_u64 v[6:7], v[2:3], 0, v[210:211]
	global_load_dwordx4 v[136:139], v[4:5], off
	global_load_dwordx4 v[140:143], v[6:7], off
	v_lshl_add_u64 v[4:5], v[0:1], 0, v[212:213]
	v_lshl_add_u64 v[0:1], v[0:1], 0, v[214:215]
	v_lshl_add_u64 v[6:7], v[2:3], 0, v[212:213]
	global_load_dwordx4 v[144:147], v[4:5], off
	global_load_dwordx4 v[148:151], v[6:7], off
	v_lshl_add_u64 v[2:3], v[2:3], 0, v[214:215]
	global_load_dwordx4 v[152:155], v[0:1], off
	global_load_dwordx4 v[156:159], v[2:3], off
	v_mov_b32_e32 v0, s1
	ds_read_b32 v0, v0
	s_ashr_i32 s1, s0, 31
	s_waitcnt lgkmcnt(0)
	v_readfirstlane_b32 s7, v0
	s_sub_i32 s8, s6, s7
	s_cmp_lg_u32 s8, 0
	s_cselect_b64 s[6:7], -1, 0
	s_cmp_eq_u32 s8, 0
	s_cbranch_scc1 .LBB0_844
	s_lshl_b32 s9, s8, 8
	s_waitcnt vmcnt(16)
	v_subrev_u32_e32 v0, s9, v20
	v_add_u32_e32 v195, 0x100, v0
	s_and_b64 vcc, exec, s[6:7]
	s_cbranch_vccz .LBB0_845
